# v49 plus nt (non-temporal) hint on the P0 colmax and quant passes' streaming f32 weight loads
# speedup vs baseline: 1.0077x; 1.0077x over previous
.LBB0_145:
	v_lshl_add_u64 v[6:7], s[6:7], 0, v[68:69]
	s_lshl_b64 s[36:37], s[30:31], 2
	v_lshl_add_u64 v[6:7], v[6:7], 0, s[36:37]
	v_lshl_add_u64 v[14:15], v[6:7], 0, s[36:37]
	global_load_dwordx4 v[10:13], v[6:7], off nt
	s_nop 0
	global_load_dwordx4 v[6:9], v[14:15], off nt
	v_cndmask_b32_e64 v16, 0, 1, s[38:39]
	v_cmp_ne_u32_e64 s[6:7], 1, v16
	s_andn2_b64 vcc, exec, s[38:39]
	v_mov_b32_e32 v86, 1.0
	s_cbranch_vccnz .LBB0_147
	s_lshl_b64 s[38:39], s[28:29], 2
	s_add_u32 s38, s26, s38
	s_addc_u32 s39, s27, s39
	global_load_dwordx2 v[76:77], v69, s[38:39] offset:8
	s_waitcnt vmcnt(0)
	v_mov_b32_e32 v86, v77
.LBB0_147:
	v_lshl_add_u64 v[14:15], v[14:15], 0, s[36:37]
	v_lshl_add_u64 v[22:23], v[14:15], 0, s[36:37]
	global_load_dwordx4 v[14:17], v[14:15], off nt
	s_nop 0
	global_load_dwordx4 v[18:21], v[22:23], off nt
	s_and_b64 vcc, exec, s[6:7]
	v_mov_b32_e32 v82, 1.0
	s_cbranch_vccnz .LBB0_149
	s_lshl_b64 s[38:39], s[28:29], 2
	s_add_u32 s38, s26, s38
	s_addc_u32 s39, s27, s39
	global_load_dwordx2 v[92:93], v69, s[38:39] offset:16
	s_waitcnt vmcnt(0)
	v_mov_b32_e32 v90, v93
	s_branch .LBB0_150

.LBB0_150:
	v_lshl_add_u64 v[24:25], v[22:23], 0, s[36:37]
	v_lshl_add_u64 v[22:23], v[24:25], 0, s[36:37]
	global_load_dwordx4 v[30:33], v[24:25], off nt
	global_load_dwordx4 v[26:29], v[22:23], off nt
	s_and_b64 vcc, exec, s[6:7]
	v_mov_b32_e32 v96, 1.0
	s_cbranch_vccnz .LBB0_152
	s_lshl_b64 s[38:39], s[28:29], 2
	s_add_u32 s38, s26, s38
	s_addc_u32 s39, s27, s39
	global_load_dwordx2 v[82:83], v69, s[38:39] offset:24
	s_waitcnt vmcnt(0)
	v_mov_b32_e32 v96, v83
.LBB0_152:
	v_lshl_add_u64 v[22:23], v[22:23], 0, s[36:37]
	global_load_dwordx4 v[22:25], v[22:23], off nt
	s_lshl_b64 s[36:37], s[28:29], 2
	s_add_u32 s28, s36, 32
	s_addc_u32 s29, s37, 0
	s_add_u32 s26, s26, s28
	s_addc_u32 s27, s27, s29
	v_lshl_add_u64 v[34:35], s[34:35], 0, v[70:71]
	s_mul_i32 s34, s31, s28
	s_mul_i32 s29, s30, s29
	v_mov_b32_e32 v36, s28
	s_add_i32 s34, s29, s34
	v_mad_u64_u32 v[84:85], s[28:29], s30, v36, v[34:35]
	s_lshl_b64 s[28:29], s[30:31], 5
	v_add_u32_e32 v85, s34, v85
	s_add_u32 s34, s36, 36
	s_addc_u32 s35, s37, 0
	s_mul_i32 s38, s31, s34
	s_mul_i32 s35, s30, s35
	v_mov_b32_e32 v36, s34
	s_add_i32 s38, s35, s38
	v_mad_u64_u32 v[88:89], s[34:35], s30, v36, v[34:35]
	s_add_u32 s34, s36, 44
	s_addc_u32 s35, s37, 0
	v_add_u32_e32 v89, s38, v89
	s_mul_i32 s38, s31, s34
	s_mul_i32 s35, s30, s35
	v_mov_b32_e32 v36, s34
	s_add_i32 s38, s35, s38
	v_mad_u64_u32 v[94:95], s[34:35], s30, v36, v[34:35]
	s_add_u32 s34, s36, 48
	s_addc_u32 s35, s37, 0
	v_add_u32_e32 v95, s38, v95
	s_mul_i32 s38, s31, s34
	s_mul_i32 s35, s30, s35
	v_mov_b32_e32 v36, s34
	s_add_i32 s38, s35, s38
	v_mad_u64_u32 v[98:99], s[34:35], s30, v36, v[34:35]
	s_add_u32 s34, s36, 52
	s_addc_u32 s35, s37, 0
	v_add_u32_e32 v99, s38, v99
	s_mul_i32 s38, s31, s34
	s_mul_i32 s35, s30, s35
	v_mov_b32_e32 v36, s34
	s_add_i32 s38, s35, s38
	v_mad_u64_u32 v[100:101], s[34:35], s30, v36, v[34:35]
	s_add_u32 s34, s36, 56
	s_addc_u32 s35, s37, 0
	v_add_u32_e32 v101, s38, v101
	s_mul_i32 s38, s31, s34
	s_mul_i32 s35, s30, s35
	v_mov_b32_e32 v36, s34
	s_add_i32 s38, s35, s38
	v_mad_u64_u32 v[102:103], s[34:35], s30, v36, v[34:35]
	s_add_u32 s34, s36, 60
	s_addc_u32 s35, s37, 0
	v_add_u32_e32 v103, s38, v103
	s_mul_i32 s38, s31, s34
	s_mul_i32 s35, s30, s35
	v_mov_b32_e32 v36, s34
	s_add_i32 s38, s35, s38
	v_mad_u64_u32 v[104:105], s[34:35], s30, v36, v[34:35]
	s_add_u32 s34, s36, 40
	s_addc_u32 s35, s37, 0
	s_mul_i32 s31, s31, s34
	s_mul_i32 s35, s30, s35
	v_mov_b32_e32 v36, s34
	s_add_i32 s35, s35, s31
	v_mad_u64_u32 v[106:107], s[30:31], s30, v36, v[34:35]
	v_add_u32_e32 v105, s38, v105
	v_add_u32_e32 v107, s35, v107
	v_mov_b32_e32 v73, 0
	s_mov_b32 s34, 0
	v_mov_b32_e32 v75, 0
	v_mov_b32_e32 v77, 0
	v_mov_b32_e32 v81, 0
.LBB0_153:
	v_lshl_add_u64 v[34:35], v[84:85], 0, s[24:25]
	global_load_dwordx4 v[34:37], v[34:35], off nt
	s_and_b64 vcc, exec, s[6:7]
	v_lshl_add_u64 v[42:43], v[88:89], 0, s[24:25]
	s_cbranch_vccnz .LBB0_167
	global_load_dwordx4 v[38:41], v[42:43], off nt
	global_load_dwordx2 v[108:109], v69, s[26:27]
	s_cbranch_execnz .LBB0_156
.LBB0_155:
	global_load_dwordx4 v[38:41], v[42:43], off nt
	v_mov_b32_e32 v109, 1.0
	v_mov_b32_e32 v108, 1.0
.LBB0_156:
	v_lshl_add_u64 v[42:43], v[106:107], 0, s[24:25]
	global_load_dwordx4 v[42:45], v[42:43], off nt
	s_and_b64 vcc, exec, s[6:7]
	v_lshl_add_u64 v[50:51], v[94:95], 0, s[24:25]
	s_cbranch_vccnz .LBB0_168
	global_load_dwordx4 v[46:49], v[50:51], off nt
	global_load_dwordx2 v[110:111], v69, s[26:27] offset:8
	s_cbranch_execnz .LBB0_159
.LBB0_158:
	global_load_dwordx4 v[46:49], v[50:51], off nt
	v_mov_b32_e32 v111, 1.0
	v_mov_b32_e32 v110, 1.0
.LBB0_159:
	v_lshl_add_u64 v[50:51], v[98:99], 0, s[24:25]
	global_load_dwordx4 v[50:53], v[50:51], off nt
	s_and_b64 vcc, exec, s[6:7]
	v_lshl_add_u64 v[58:59], v[100:101], 0, s[24:25]
	s_cbranch_vccnz .LBB0_169
	global_load_dwordx4 v[54:57], v[58:59], off nt
	global_load_dwordx2 v[112:113], v69, s[26:27] offset:16
	s_cbranch_execnz .LBB0_162
.LBB0_161:
	global_load_dwordx4 v[54:57], v[58:59], off nt
	v_mov_b32_e32 v113, 1.0
	v_mov_b32_e32 v112, 1.0
.LBB0_162:
	v_lshl_add_u64 v[58:59], v[102:103], 0, s[24:25]
	global_load_dwordx4 v[58:61], v[58:59], off nt
	s_and_b64 vcc, exec, s[6:7]
	v_lshl_add_u64 v[116:117], v[104:105], 0, s[24:25]
	s_cbranch_vccnz .LBB0_170
	global_load_dwordx4 v[62:65], v[116:117], off nt
	global_load_dwordx2 v[114:115], v69, s[26:27] offset:24
	s_cbranch_execnz .LBB0_165
.LBB0_164:
	global_load_dwordx4 v[62:65], v[116:117], off nt
	v_mov_b32_e32 v115, 1.0
	v_mov_b32_e32 v114, 1.0

.LBB0_259:
	s_load_dwordx2 s[26:27], s[26:27], 0x0
	v_lshrrev_b32_e32 v77, 3, v187
	v_add_u32_e32 v6, s49, v77
	v_ashrrev_i32_e32 v7, 31, v6
	v_mul_lo_u32 v4, s24, v7
	v_mul_lo_u32 v5, s25, v6
	v_mad_u64_u32 v[2:3], s[28:29], s24, v6, 0
	v_add3_u32 v3, v3, v4, v5
	v_and_b32_e32 v1, 28, v66
	s_waitcnt lgkmcnt(0)
	v_lshl_add_u64 v[2:3], v[2:3], 2, s[26:27]
	s_ashr_i32 s9, s8, 31
	v_mov_b32_e32 v75, 0
	v_lshl_add_u64 v[2:3], s[8:9], 2, v[2:3]
	v_lshlrev_b32_e32 v74, 2, v1
	v_lshl_add_u64 v[2:3], v[2:3], 0, v[74:75]
	global_load_dwordx4 v[2:5], v[2:3], off nt
	s_cmp_lg_u64 s[6:7], 0
	v_mov_b32_e32 v76, 1.0
	s_cselect_b64 s[28:29], -1, 0
	s_cmp_eq_u64 s[6:7], 0
	v_lshl_add_u64 v[34:35], v[6:7], 2, s[6:7]
	v_mov_b32_e32 v78, 1.0
	s_cbranch_scc1 .LBB0_261
	global_load_dword v78, v[34:35], off
.LBB0_261:
	v_or_b32_e32 v79, 8, v77
	v_add_u32_e32 v1, s49, v79
	v_ashrrev_i32_e32 v6, 31, v1
	v_mul_lo_u32 v8, s24, v6
	v_mul_lo_u32 v9, s25, v1
	v_mad_u64_u32 v[6:7], s[6:7], s24, v1, 0
	v_add3_u32 v7, v7, v8, v9
	v_lshl_add_u64 v[6:7], v[6:7], 2, s[26:27]
	v_lshl_add_u64 v[6:7], s[8:9], 2, v[6:7]
	v_lshl_add_u64 v[6:7], v[6:7], 0, v[74:75]
	global_load_dwordx4 v[6:9], v[6:7], off nt
	v_cndmask_b32_e64 v1, 0, 1, s[28:29]
	v_cmp_ne_u32_e64 s[6:7], 1, v1
	s_andn2_b64 vcc, exec, s[28:29]
	s_cbranch_vccnz .LBB0_263
	global_load_dword v76, v[34:35], off offset:32
.LBB0_263:
	v_or_b32_e32 v81, 16, v77
	v_add_u32_e32 v1, s49, v81
	v_ashrrev_i32_e32 v10, 31, v1
	v_mul_lo_u32 v12, s24, v10
	v_mul_lo_u32 v13, s25, v1
	v_mad_u64_u32 v[10:11], s[28:29], s24, v1, 0
	v_add3_u32 v11, v11, v12, v13
	v_lshl_add_u64 v[10:11], v[10:11], 2, s[26:27]
	v_lshl_add_u64 v[10:11], s[8:9], 2, v[10:11]
	v_mov_b32_e32 v75, 0
	v_lshl_add_u64 v[10:11], v[10:11], 0, v[74:75]
	global_load_dwordx4 v[10:13], v[10:11], off nt
	v_mov_b32_e32 v80, 1.0
	s_and_b64 vcc, exec, s[6:7]
	v_mov_b32_e32 v82, 1.0
	s_cbranch_vccnz .LBB0_265
	global_load_dword v82, v[34:35], off offset:64
.LBB0_265:
	v_or_b32_e32 v83, 24, v77
	v_add_u32_e32 v1, s49, v83
	v_ashrrev_i32_e32 v14, 31, v1
	v_mul_lo_u32 v16, s24, v14
	v_mul_lo_u32 v17, s25, v1
	v_mad_u64_u32 v[14:15], s[28:29], s24, v1, 0
	v_add3_u32 v15, v15, v16, v17
	v_lshl_add_u64 v[14:15], v[14:15], 2, s[26:27]
	v_lshl_add_u64 v[14:15], s[8:9], 2, v[14:15]
	v_lshl_add_u64 v[14:15], v[14:15], 0, v[74:75]
	global_load_dwordx4 v[14:17], v[14:15], off nt
	s_and_b64 vcc, exec, s[6:7]
	s_cbranch_vccnz .LBB0_267
	global_load_dword v80, v[34:35], off offset:96
.LBB0_267:
	v_or_b32_e32 v85, 32, v77
	v_add_u32_e32 v1, s49, v85
	v_ashrrev_i32_e32 v18, 31, v1
	v_mul_lo_u32 v20, s24, v18
	v_mul_lo_u32 v21, s25, v1
	v_mad_u64_u32 v[18:19], s[28:29], s24, v1, 0
	v_add3_u32 v19, v19, v20, v21
	v_lshl_add_u64 v[18:19], v[18:19], 2, s[26:27]
	v_lshl_add_u64 v[18:19], s[8:9], 2, v[18:19]
	v_mov_b32_e32 v75, 0
	v_lshl_add_u64 v[18:19], v[18:19], 0, v[74:75]
	global_load_dwordx4 v[18:21], v[18:19], off nt
	v_mov_b32_e32 v84, 1.0
	s_and_b64 vcc, exec, s[6:7]
	v_mov_b32_e32 v86, 1.0
	s_cbranch_vccnz .LBB0_269
	global_load_dword v86, v[34:35], off offset:128
.LBB0_269:
	v_or_b32_e32 v87, 40, v77
	v_add_u32_e32 v1, s49, v87
	v_ashrrev_i32_e32 v22, 31, v1
	v_mul_lo_u32 v24, s24, v22
	v_mul_lo_u32 v25, s25, v1
	v_mad_u64_u32 v[22:23], s[28:29], s24, v1, 0
	v_add3_u32 v23, v23, v24, v25
	v_lshl_add_u64 v[22:23], v[22:23], 2, s[26:27]
	v_lshl_add_u64 v[22:23], s[8:9], 2, v[22:23]
	v_lshl_add_u64 v[22:23], v[22:23], 0, v[74:75]
	global_load_dwordx4 v[22:25], v[22:23], off nt
	s_and_b64 vcc, exec, s[6:7]
	s_cbranch_vccnz .LBB0_271
	global_load_dword v84, v[34:35], off offset:160
.LBB0_271:
	v_or_b32_e32 v89, 48, v77
	v_add_u32_e32 v1, s49, v89
	v_ashrrev_i32_e32 v26, 31, v1
	v_mul_lo_u32 v28, s24, v26
	v_mul_lo_u32 v29, s25, v1
	v_mad_u64_u32 v[26:27], s[28:29], s24, v1, 0
	v_add3_u32 v27, v27, v28, v29
	v_lshl_add_u64 v[26:27], v[26:27], 2, s[26:27]
	v_lshl_add_u64 v[26:27], s[8:9], 2, v[26:27]
	v_mov_b32_e32 v75, 0
	v_lshl_add_u64 v[26:27], v[26:27], 0, v[74:75]
	global_load_dwordx4 v[26:29], v[26:27], off nt
	v_mov_b32_e32 v88, 1.0
	s_and_b64 vcc, exec, s[6:7]
	v_mov_b32_e32 v90, 1.0
	s_cbranch_vccnz .LBB0_273
	global_load_dword v90, v[34:35], off offset:192
.LBB0_273:
	v_or_b32_e32 v91, 56, v77
	v_add_u32_e32 v1, s49, v91
	v_ashrrev_i32_e32 v30, 31, v1
	v_mul_lo_u32 v32, s24, v30
	v_mul_lo_u32 v33, s25, v1
	v_mad_u64_u32 v[30:31], s[24:25], s24, v1, 0
	v_add3_u32 v31, v31, v32, v33
	v_lshl_add_u64 v[30:31], v[30:31], 2, s[26:27]
	v_lshl_add_u64 v[30:31], s[8:9], 2, v[30:31]
	v_lshl_add_u64 v[30:31], v[30:31], 0, v[74:75]
	global_load_dwordx4 v[30:33], v[30:31], off nt
	s_and_b64 vcc, exec, s[6:7]
	s_cbranch_vccnz .LBB0_275
	global_load_dword v88, v[34:35], off offset:224

.LBB0_299:
	s_load_dwordx2 s[58:59], s[58:59], 0x0
	v_add_u32_e32 v44, s66, v77
	v_ashrrev_i32_e32 v45, 31, v44
	v_mul_lo_u32 v1, s42, v45
	v_mul_lo_u32 v40, s43, v44
	v_mad_u64_u32 v[38:39], s[60:61], s42, v44, 0
	v_add3_u32 v39, v39, v1, v40
	s_waitcnt lgkmcnt(0)
	v_lshl_add_u64 v[38:39], v[38:39], 2, s[58:59]
	s_ashr_i32 s41, s40, 31
	v_lshl_add_u64 v[38:39], s[40:41], 2, v[38:39]
	v_lshl_add_u64 v[38:39], v[38:39], 0, v[74:75]
	global_load_dwordx4 v[38:41], v[38:39], off nt
	s_cmp_lg_u64 s[8:9], 0
	v_add_u32_e32 v42, s66, v79
	s_cselect_b64 s[62:63], -1, 0
	s_cmp_eq_u64 s[8:9], 0
	v_lshl_add_u64 v[66:67], v[44:45], 2, s[8:9]
	v_ashrrev_i32_e32 v1, 31, v42
	s_cbranch_scc1 .LBB0_316
	global_load_dword v100, v[66:67], off
	global_load_dword v101, v[66:67], off offset:32
	s_cbranch_execnz .LBB0_302

.LBB0_302:
	v_mul_lo_u32 v1, v1, s42
	v_mul_lo_u32 v44, v42, s43
	v_mad_u64_u32 v[42:43], s[8:9], v42, s42, 0
	v_add3_u32 v43, v43, v44, v1
	v_add_u32_e32 v1, s66, v81
	v_ashrrev_i32_e32 v44, 31, v1
	v_mul_lo_u32 v46, s42, v44
	v_mul_lo_u32 v47, s43, v1
	v_mad_u64_u32 v[44:45], s[8:9], s42, v1, 0
	v_add3_u32 v45, v45, v46, v47
	v_lshl_add_u64 v[42:43], v[42:43], 2, s[58:59]
	s_lshl_b64 s[60:61], s[40:41], 2
	v_lshl_add_u64 v[44:45], v[44:45], 2, s[58:59]
	v_lshl_add_u64 v[42:43], v[42:43], 0, s[60:61]
	v_lshl_add_u64 v[44:45], v[44:45], 0, s[60:61]
	v_lshl_add_u64 v[42:43], v[42:43], 0, v[74:75]
	v_lshl_add_u64 v[44:45], v[44:45], 0, v[74:75]
	global_load_dwordx4 v[46:49], v[42:43], off nt
	s_nop 0
	global_load_dwordx4 v[42:45], v[44:45], off nt
	v_cndmask_b32_e64 v1, 0, 1, s[62:63]
	v_add_u32_e32 v50, s66, v83
	v_cmp_ne_u32_e64 s[8:9], 1, v1
	s_andn2_b64 vcc, exec, s[62:63]
	v_ashrrev_i32_e32 v1, 31, v50
	s_cbranch_vccnz .LBB0_317
	global_load_dword v102, v[66:67], off offset:64
	global_load_dword v103, v[66:67], off offset:96
	s_cbranch_execnz .LBB0_305

.LBB0_305:
	v_mul_lo_u32 v1, v1, s42
	v_mul_lo_u32 v52, v50, s43
	v_mad_u64_u32 v[50:51], s[62:63], v50, s42, 0
	v_add3_u32 v51, v51, v52, v1
	v_add_u32_e32 v1, s66, v85
	v_ashrrev_i32_e32 v52, 31, v1
	v_mul_lo_u32 v54, s42, v52
	v_mul_lo_u32 v55, s43, v1
	v_mad_u64_u32 v[52:53], s[62:63], s42, v1, 0
	v_add3_u32 v53, v53, v54, v55
	v_lshl_add_u64 v[50:51], v[50:51], 2, s[58:59]
	v_lshl_add_u64 v[52:53], v[52:53], 2, s[58:59]
	v_lshl_add_u64 v[50:51], v[50:51], 0, s[60:61]
	v_lshl_add_u64 v[52:53], v[52:53], 0, s[60:61]
	v_lshl_add_u64 v[50:51], v[50:51], 0, v[74:75]
	v_lshl_add_u64 v[52:53], v[52:53], 0, v[74:75]
	global_load_dwordx4 v[54:57], v[50:51], off nt
	s_nop 0
	global_load_dwordx4 v[50:53], v[52:53], off nt
	v_add_u32_e32 v58, s66, v87
	s_and_b64 vcc, exec, s[8:9]
	v_ashrrev_i32_e32 v1, 31, v58
	s_cbranch_vccnz .LBB0_318
	global_load_dword v104, v[66:67], off offset:128
	global_load_dword v105, v[66:67], off offset:160
	s_cbranch_execnz .LBB0_308

.LBB0_308:
	v_mul_lo_u32 v1, v1, s42
	v_mul_lo_u32 v60, v58, s43
	v_mad_u64_u32 v[58:59], s[62:63], v58, s42, 0
	v_add3_u32 v59, v59, v60, v1
	v_add_u32_e32 v1, s66, v89
	v_ashrrev_i32_e32 v60, 31, v1
	v_mul_lo_u32 v62, s42, v60
	v_mul_lo_u32 v63, s43, v1
	v_mad_u64_u32 v[60:61], s[62:63], s42, v1, 0
	v_add3_u32 v61, v61, v62, v63
	v_lshl_add_u64 v[58:59], v[58:59], 2, s[58:59]
	v_lshl_add_u64 v[60:61], v[60:61], 2, s[58:59]
	v_lshl_add_u64 v[58:59], v[58:59], 0, s[60:61]
	v_lshl_add_u64 v[60:61], v[60:61], 0, s[60:61]
	v_lshl_add_u64 v[58:59], v[58:59], 0, v[74:75]
	v_lshl_add_u64 v[60:61], v[60:61], 0, v[74:75]
	global_load_dwordx4 v[62:65], v[58:59], off nt
	s_nop 0
	global_load_dwordx4 v[58:61], v[60:61], off nt
	v_add_u32_e32 v68, s66, v91
	s_and_b64 vcc, exec, s[8:9]
	v_ashrrev_i32_e32 v1, 31, v68
	s_cbranch_vccnz .LBB0_319
	global_load_dword v106, v[66:67], off offset:192
	global_load_dword v107, v[66:67], off offset:224
	s_cbranch_execnz .LBB0_311

.LBB0_311:
	s_add_u32 s17, s14, s46
	s_addc_u32 s46, s15, s47
	s_add_u32 s8, s14, s44
	s_addc_u32 s9, s15, s45
	v_mul_lo_u32 v1, v1, s42
	v_mul_lo_u32 v69, v68, s43
	v_mad_u64_u32 v[66:67], s[42:43], v68, s42, 0
	s_add_u32 s38, s14, s38
	v_add3_u32 v67, v67, v69, v1
	s_addc_u32 s39, s15, s39
	v_lshl_add_u64 v[66:67], v[66:67], 2, s[58:59]
	s_ashr_i32 s37, s36, 31
	v_lshl_add_u64 v[66:67], s[40:41], 2, v[66:67]
	s_lshl_b64 s[40:41], s[36:37], 2
	s_add_u32 s40, s17, s40
	s_addc_u32 s41, s46, s41
	v_mov_b32_e32 v95, v75
	v_lshl_add_u64 v[66:67], v[66:67], 0, v[74:75]
	v_lshl_add_u64 v[70:71], s[40:41], 0, v[94:95]
	global_load_dwordx4 v[66:69], v[66:67], off nt
	s_nop 0
	flat_load_dwordx4 v[70:73], v[70:71]
